# grid barrier tail rewritten: same per-XCD arrival counter and wbl2 release by the last arriver, but all blocks wait on the monotonic top counter directly (generation kept in LDS) instead of the TOPGEN
# speedup vs baseline: 1.0906x; 1.0129x over previous
.LBB0_75:
	s_lshl_b32 s98, s18, 8
	s_add_u32 s98, s2, s98
	s_addc_u32 s99, s3, 0
	v_mov_b32_e32 v1, 0
	v_mov_b32_e32 v3, 1
	v_mov_b32_e32 v6, 0x1000
	ds_read_b32 v4, v1 offset:65528
	global_atomic_add v5, v6, v3, s[98:99] offset:1024 sc0
	s_waitcnt lgkmcnt(0)
	v_add_u32_e32 v4, 1, v4
	ds_write_b32 v1, v4 offset:65528
	v_mul_lo_u32 v7, v4, v2
	v_mul_lo_u32 v8, v4, v0
	v_mov_b32_e32 v9, 0x3000
	s_waitcnt vmcnt(0)
	v_add_u32_e32 v5, 1, v5
	v_cmp_eq_u32_e32 vcc, v5, v7
	s_cbranch_vccz .Lfb_spin_0
	buffer_wbl2 sc1
	s_waitcnt vmcnt(0) lgkmcnt(0)
	global_atomic_add v9, v3, s[2:3] offset:1024
.Lfb_spin_0:
	global_load_dword v5, v9, s[2:3] offset:1024 sc1
	s_waitcnt vmcnt(0)
	v_cmp_lt_u32_e32 vcc, v5, v8
	s_cbranch_vccz .Lfb_done_0
	s_sleep 1
	s_branch .Lfb_spin_0
.Lfb_done_0:
	buffer_inv sc1
	s_waitcnt vmcnt(0) lgkmcnt(0)

.LBB0_789:
	s_lshl_b32 s98, s20, 8
	s_add_u32 s98, s4, s98
	s_addc_u32 s99, s5, 0
	v_mov_b32_e32 v1, 0
	v_mov_b32_e32 v3, 1
	v_mov_b32_e32 v6, 0x1000
	ds_read_b32 v4, v1 offset:65528
	global_atomic_add v5, v6, v3, s[98:99] offset:1024 sc0
	s_waitcnt lgkmcnt(0)
	v_add_u32_e32 v4, 1, v4
	ds_write_b32 v1, v4 offset:65528
	v_mul_lo_u32 v7, v4, v2
	v_mul_lo_u32 v8, v4, v0
	v_mov_b32_e32 v9, 0x3000
	s_waitcnt vmcnt(0)
	v_add_u32_e32 v5, 1, v5
	v_cmp_eq_u32_e32 vcc, v5, v7
	s_cbranch_vccz .Lfb_spin_5
	buffer_wbl2 sc1
	s_waitcnt vmcnt(0) lgkmcnt(0)
	global_atomic_add v9, v3, s[4:5] offset:1024
.Lfb_spin_5:
	global_load_dword v5, v9, s[4:5] offset:1024 sc1
	s_waitcnt vmcnt(0)
	v_cmp_lt_u32_e32 vcc, v5, v8
	s_cbranch_vccz .Lfb_done_5
	s_sleep 1
	s_branch .Lfb_spin_5
